# dynamic tile queue (one atomic counter per phase and XCD) for the four GEMM phases with more than 4 tiles per workgroup (1, 8, 11, 17): workgroups that run ahead take more tiles
# baseline (speedup 1.0000x reference)
; DI void phase_prep(const Ctx& c, char* smem) {
;   const Params& p = c.p; (void)p;
;   if (blockIdx.x == 0 && TIDX == 0) { for (int i_ = 0; i_ < 17; ++i_) __hip_atomic_store((unsigned*)(p.ws + OFF_BAR) + 64 * i_, 0u, __ATOMIC_RELAXED, __HIP_MEMORY_SCOPE_AGENT); }
.LBB0_3:
	v_mbcnt_lo_u32_b32 v2, -1, 0
	v_mbcnt_hi_u32_b32 v22, -1, v2
	s_and_b32 s0, s72, 0xffffffc0
	v_sub_u32_e32 v2, 0, v22
	v_cmp_eq_u32_e32 vcc, s0, v2
	s_and_saveexec_b64 s[0:1], vcc
	s_cbranch_execz .LBB0_5
	v_mov_b32_e32 v2, 0x1fe00000
	v_mov_b32_e32 v3, 0
	global_store_dword v2, v3, s[92:93] sc1
	global_store_dword v2, v3, s[92:93] offset:256 sc1
	global_store_dword v2, v3, s[92:93] offset:512 sc1
	global_store_dword v2, v3, s[92:93] offset:768 sc1
	global_store_dword v2, v3, s[92:93] offset:1024 sc1
	global_store_dword v2, v3, s[92:93] offset:1280 sc1
	global_store_dword v2, v3, s[92:93] offset:1536 sc1
	global_store_dword v2, v3, s[92:93] offset:1792 sc1
	global_store_dword v2, v3, s[92:93] offset:2048 sc1
	global_store_dword v2, v3, s[92:93] offset:2304 sc1
	global_store_dword v2, v3, s[92:93] offset:2560 sc1
	global_store_dword v2, v3, s[92:93] offset:2816 sc1
	global_store_dword v2, v3, s[92:93] offset:3072 sc1
	global_store_dword v2, v3, s[92:93] offset:3328 sc1
	global_store_dword v2, v3, s[92:93] offset:3584 sc1
	global_store_dword v2, v3, s[92:93] offset:3840 sc1
	global_store_dword v2, v3, s[92:93] offset:32 sc1
	global_store_dword v2, v3, s[92:93] offset:36 sc1
	global_store_dword v2, v3, s[92:93] offset:40 sc1
	global_store_dword v2, v3, s[92:93] offset:44 sc1
	global_store_dword v2, v3, s[92:93] offset:48 sc1
	global_store_dword v2, v3, s[92:93] offset:52 sc1
	global_store_dword v2, v3, s[92:93] offset:56 sc1
	global_store_dword v2, v3, s[92:93] offset:60 sc1
	global_store_dword v2, v3, s[92:93] offset:288 sc1
	global_store_dword v2, v3, s[92:93] offset:292 sc1
	global_store_dword v2, v3, s[92:93] offset:296 sc1
	global_store_dword v2, v3, s[92:93] offset:300 sc1
	global_store_dword v2, v3, s[92:93] offset:304 sc1
	global_store_dword v2, v3, s[92:93] offset:308 sc1
	global_store_dword v2, v3, s[92:93] offset:312 sc1
	global_store_dword v2, v3, s[92:93] offset:316 sc1
	global_store_dword v2, v3, s[92:93] offset:544 sc1
	global_store_dword v2, v3, s[92:93] offset:548 sc1
	global_store_dword v2, v3, s[92:93] offset:552 sc1
	global_store_dword v2, v3, s[92:93] offset:556 sc1
	global_store_dword v2, v3, s[92:93] offset:560 sc1
	global_store_dword v2, v3, s[92:93] offset:564 sc1
	global_store_dword v2, v3, s[92:93] offset:568 sc1
	global_store_dword v2, v3, s[92:93] offset:572 sc1
	global_store_dword v2, v3, s[92:93] offset:800 sc1
	global_store_dword v2, v3, s[92:93] offset:804 sc1
	global_store_dword v2, v3, s[92:93] offset:808 sc1
	global_store_dword v2, v3, s[92:93] offset:812 sc1
	global_store_dword v2, v3, s[92:93] offset:816 sc1
	global_store_dword v2, v3, s[92:93] offset:820 sc1
	global_store_dword v2, v3, s[92:93] offset:824 sc1
	global_store_dword v2, v3, s[92:93] offset:828 sc1
	v_mov_b32_e32 v2, 0x1fe01000
	global_store_dword v2, v3, s[92:93] sc1

; template <class Epi>
; DI void gemm_phase(char* smem, const bf16_t* A0, int lda0, int ksplit, const bf16_t* A1, int lda1, const bf16_t* Bt, int K, int nN, const Epi& epi, int tid) {
;   const int G = gridDim.x;
;   if ((G & 7) == 0) {
;     const int x = blockIdx.x & 7, l = blockIdx.x >> 3, L = G >> 3, per = 8 * nN, tot = 2 * per;
;     for (int q = l; q < tot; q += L) { const int rgl = q / per, rem = q % per, ct = rem >> 3, rt = (x * 2 + rgl) * 8 + (rem & 7);
.Lg1_prio:
	s_lshr_b32 s29, s96, 3
	s_and_b32 s101, s96, 7
	s_lshl_b32 s101, s101, 1
	s_waitcnt lgkmcnt(0)
	s_lshl_b32 s23, s101, 1
	s_add_u32 s23, s23, 0x1fe00020
	s_add_u32 s6, s92, s23
	s_addc_u32 s7, s93, 0
	v_mov_b32_e32 v240, 0
	v_mov_b32_e32 v241, 1
	v_mov_b32_e32 v243, 0x13600

; template <class Epi>
; DI void gemm_phase(char* smem, const bf16_t* A0, int lda0, int ksplit, const bf16_t* A1, int lda1, const bf16_t* Bt, int K, int nN, const Epi& epi, int tid) {
;     ...
;     const int x = blockIdx.x & 7, l = blockIdx.x >> 3, L = G >> 3, per = 8 * nN, tot = 2 * per;
;     for (int q = l; q < tot; q += L) { const int rgl = q / per, rem = q % per, ct = rem >> 3, rt = (x * 2 + rgl) * 8 + (rem & 7);
;       gemm_tile(smem, A0, lda0, ksplit, A1, lda1, Bt, K, rt * 256, ct * 128, epi, tid); }
.Lg1_epi:
	s_cmp_lt_u32 s72, 64
	s_cbranch_scc0 .Lg1_dynA
	s_mov_b64 exec, 1
	global_atomic_add v242, v240, v241, s[6:7] sc0
	s_mov_b64 exec, -1

; template <class Epi>
; DI void gemm_phase(char* smem, const bf16_t* A0, int lda0, int ksplit, const bf16_t* A1, int lda1, const bf16_t* Bt, int K, int nN, const Epi& epi, int tid) {
;     ...
;     for (int q = l; q < tot; q += L) { const int rgl = q / per, rem = q % per, ct = rem >> 3, rt = (x * 2 + rgl) * 8 + (rem & 7);
;       gemm_tile(smem, A0, lda0, ksplit, A1, lda1, Bt, K, rt * 256, ct * 128, epi, tid); }
.Lg1_enext:
	s_cmp_lt_u32 s72, 64
	s_cbranch_scc0 .Lg1_dynB
	s_waitcnt vmcnt(16)
	v_readfirstlane_b32 s23, v242
	s_nop 3
	s_add_u32 s23, s23, 64
	v_mov_b32_e32 v244, s23
	ds_write_b32 v243, v244
.Lg1_dynB:
	s_waitcnt lgkmcnt(0)
	s_barrier
	ds_read_b32 v244, v243
	s_waitcnt lgkmcnt(0)
	v_readfirstlane_b32 s29, v244
	s_nop 3
	s_branch .Lg1_tile

; template <class Epi>
; DI void gemm_phase(char* smem, const bf16_t* A0, int lda0, int ksplit, const bf16_t* A1, int lda1, const bf16_t* Bt, int K, int nN, const Epi& epi, int tid) {
;   const int G = gridDim.x;
;   if ((G & 7) == 0) {
;     const int x = blockIdx.x & 7, l = blockIdx.x >> 3, L = G >> 3, per = 8 * nN, tot = 2 * per;
;     for (int q = l; q < tot; q += L) { const int rgl = q / per, rem = q % per, ct = rem >> 3, rt = (x * 2 + rgl) * 8 + (rem & 7);
.Lg8_prio:
	s_lshr_b32 s17, s96, 3
	s_and_b32 s20, s96, 7
	s_lshl_b32 s20, s20, 1
	s_waitcnt lgkmcnt(0)
	s_lshl_b32 s12, s20, 1
	s_add_u32 s12, s12, 0x1fe00120
	s_add_u32 s6, s92, s12
	s_addc_u32 s7, s93, 0
	v_mov_b32_e32 v240, 0
	v_mov_b32_e32 v241, 1
	v_mov_b32_e32 v243, 0x13600

; DI unsigned pack2(float lo, float hi) { const f32x2c v = {lo, hi}; return __builtin_bit_cast(unsigned, __builtin_convertvector(v, bf16x2c)); }
; template <class Epi>
; DI void gemm_tile(char* smem, const bf16_t* __restrict__ A0, int lda0, int ksplit, const bf16_t* __restrict__ A1, int lda1,
;                   const bf16_t* __restrict__ Bt, int K, int row0, int col0, const Epi& epi, int tid) {
;     ...
;   for (int m = 0; m < 8; ++m)
; #pragma unroll
;     for (int n = 0; n < 4; ++n) epi(row0 + wr * 128 + m * 16 + fr, col0 + wc * 64 + n * 16 + fq * 4, acc[m][n]);
; }
; DI void st_bf16x4(bf16_t* o, f32x4 v) { u32x2 q; q.x = pack2(v[0], v[1]); q.y = pack2(v[2], v[3]); *(u32x2*)o = q; }
.Lg8_dynA:
	s_nop 7
	s_nop 7
	s_mul_i32 s12, s18, 8192
	s_lshl_b32 s11, s13, 1
	s_add_u32 s12, s12, s11
	s_add_u32 s12, s12, 0x7800000
	s_add_u32 s4, s92, s12
	s_addc_u32 s5, s93, 0
	v_max_f32_e32 v0, 0, v0
	v_max_f32_e32 v1, 0, v1
	v_max_f32_e32 v2, 0, v2
	v_max_f32_e32 v3, 0, v3
	v_pk_mul_f32 v[0:1], v[0:1], v[0:1]
	v_pk_mul_f32 v[2:3], v[2:3], v[2:3]
	v_cvt_pk_bf16_f32 v128, v0, v1
	v_cvt_pk_bf16_f32 v129, v2, v3
	ds_write_b64 v236, v[128:129]
	v_max_f32_e32 v4, 0, v4
	v_max_f32_e32 v5, 0, v5
	v_max_f32_e32 v6, 0, v6
	v_max_f32_e32 v7, 0, v7
	v_pk_mul_f32 v[4:5], v[4:5], v[4:5]
	v_pk_mul_f32 v[6:7], v[6:7], v[6:7]
	v_cvt_pk_bf16_f32 v130, v4, v5
	v_cvt_pk_bf16_f32 v131, v6, v7
	ds_write_b64 v236, v[130:131] offset:32
	v_max_f32_e32 v8, 0, v8
	v_max_f32_e32 v9, 0, v9
	v_max_f32_e32 v10, 0, v10
	v_max_f32_e32 v11, 0, v11
	v_pk_mul_f32 v[8:9], v[8:9], v[8:9]
	v_pk_mul_f32 v[10:11], v[10:11], v[10:11]
	v_cvt_pk_bf16_f32 v132, v8, v9
	v_cvt_pk_bf16_f32 v133, v10, v11
	ds_write_b64 v236, v[132:133] offset:64
	v_max_f32_e32 v12, 0, v12
	v_max_f32_e32 v13, 0, v13
	v_max_f32_e32 v14, 0, v14
	v_max_f32_e32 v15, 0, v15
	v_pk_mul_f32 v[12:13], v[12:13], v[12:13]
	v_pk_mul_f32 v[14:15], v[14:15], v[14:15]
	v_cvt_pk_bf16_f32 v134, v12, v13
	v_cvt_pk_bf16_f32 v135, v14, v15
	ds_write_b64 v236, v[134:135] offset:96
	v_max_f32_e32 v16, 0, v16
	v_max_f32_e32 v17, 0, v17
	v_max_f32_e32 v18, 0, v18
	v_max_f32_e32 v19, 0, v19
	v_pk_mul_f32 v[16:17], v[16:17], v[16:17]
	v_pk_mul_f32 v[18:19], v[18:19], v[18:19]
	v_cvt_pk_bf16_f32 v136, v16, v17
	v_cvt_pk_bf16_f32 v137, v18, v19
	ds_write_b64 v236, v[136:137] offset:2304
	v_max_f32_e32 v20, 0, v20
	v_max_f32_e32 v21, 0, v21
	v_max_f32_e32 v22, 0, v22
	v_max_f32_e32 v23, 0, v23
	v_pk_mul_f32 v[20:21], v[20:21], v[20:21]
	v_pk_mul_f32 v[22:23], v[22:23], v[22:23]
	v_cvt_pk_bf16_f32 v138, v20, v21
	v_cvt_pk_bf16_f32 v139, v22, v23
	ds_write_b64 v236, v[138:139] offset:2336
	v_max_f32_e32 v24, 0, v24
	v_max_f32_e32 v25, 0, v25
	v_max_f32_e32 v26, 0, v26
	v_max_f32_e32 v27, 0, v27
	v_pk_mul_f32 v[24:25], v[24:25], v[24:25]
	v_pk_mul_f32 v[26:27], v[26:27], v[26:27]
	v_cvt_pk_bf16_f32 v140, v24, v25
	v_cvt_pk_bf16_f32 v141, v26, v27
	ds_write_b64 v236, v[140:141] offset:2368
	v_max_f32_e32 v28, 0, v28
	v_max_f32_e32 v29, 0, v29
	v_max_f32_e32 v30, 0, v30
	v_max_f32_e32 v31, 0, v31
	v_pk_mul_f32 v[28:29], v[28:29], v[28:29]
	v_pk_mul_f32 v[30:31], v[30:31], v[30:31]
	v_cvt_pk_bf16_f32 v142, v28, v29
	v_cvt_pk_bf16_f32 v143, v30, v31
	ds_write_b64 v236, v[142:143] offset:2400
	v_max_f32_e32 v32, 0, v32
	v_max_f32_e32 v33, 0, v33
	v_max_f32_e32 v34, 0, v34
	v_max_f32_e32 v35, 0, v35
	v_pk_mul_f32 v[32:33], v[32:33], v[32:33]
	v_pk_mul_f32 v[34:35], v[34:35], v[34:35]
	v_cvt_pk_bf16_f32 v144, v32, v33
	v_cvt_pk_bf16_f32 v145, v34, v35
	ds_write_b64 v236, v[144:145] offset:4608
	v_max_f32_e32 v36, 0, v36
	v_max_f32_e32 v37, 0, v37
	v_max_f32_e32 v38, 0, v38
	v_max_f32_e32 v39, 0, v39
	v_pk_mul_f32 v[36:37], v[36:37], v[36:37]
	v_pk_mul_f32 v[38:39], v[38:39], v[38:39]
	v_cvt_pk_bf16_f32 v146, v36, v37
	v_cvt_pk_bf16_f32 v147, v38, v39
	ds_write_b64 v236, v[146:147] offset:4640
	v_max_f32_e32 v40, 0, v40
	v_max_f32_e32 v41, 0, v41
	v_max_f32_e32 v42, 0, v42
	v_max_f32_e32 v43, 0, v43
	v_pk_mul_f32 v[40:41], v[40:41], v[40:41]
	v_pk_mul_f32 v[42:43], v[42:43], v[42:43]
	v_cvt_pk_bf16_f32 v148, v40, v41
	v_cvt_pk_bf16_f32 v149, v42, v43
	ds_write_b64 v236, v[148:149] offset:4672
	v_max_f32_e32 v44, 0, v44
	v_max_f32_e32 v45, 0, v45
	v_max_f32_e32 v46, 0, v46
	v_max_f32_e32 v47, 0, v47
	v_pk_mul_f32 v[44:45], v[44:45], v[44:45]
	v_pk_mul_f32 v[46:47], v[46:47], v[46:47]
	v_cvt_pk_bf16_f32 v150, v44, v45
	v_cvt_pk_bf16_f32 v151, v46, v47
	ds_write_b64 v236, v[150:151] offset:4704
	v_max_f32_e32 v48, 0, v48
	v_max_f32_e32 v49, 0, v49
	v_max_f32_e32 v50, 0, v50
	v_max_f32_e32 v51, 0, v51
	v_pk_mul_f32 v[48:49], v[48:49], v[48:49]
	v_pk_mul_f32 v[50:51], v[50:51], v[50:51]
	v_cvt_pk_bf16_f32 v152, v48, v49
	v_cvt_pk_bf16_f32 v153, v50, v51
	ds_write_b64 v236, v[152:153] offset:6912
	v_max_f32_e32 v52, 0, v52
	v_max_f32_e32 v53, 0, v53
	v_max_f32_e32 v54, 0, v54
	v_max_f32_e32 v55, 0, v55
	v_pk_mul_f32 v[52:53], v[52:53], v[52:53]
	v_pk_mul_f32 v[54:55], v[54:55], v[54:55]
	v_cvt_pk_bf16_f32 v154, v52, v53
	v_cvt_pk_bf16_f32 v155, v54, v55
	ds_write_b64 v236, v[154:155] offset:6944
	v_max_f32_e32 v56, 0, v56
	v_max_f32_e32 v57, 0, v57
	v_max_f32_e32 v58, 0, v58
	v_max_f32_e32 v59, 0, v59
	v_pk_mul_f32 v[56:57], v[56:57], v[56:57]
	v_pk_mul_f32 v[58:59], v[58:59], v[58:59]
	v_cvt_pk_bf16_f32 v156, v56, v57
	v_cvt_pk_bf16_f32 v157, v58, v59
	ds_write_b64 v236, v[156:157] offset:6976
	v_max_f32_e32 v60, 0, v60
	v_max_f32_e32 v61, 0, v61
	v_max_f32_e32 v62, 0, v62
	v_max_f32_e32 v63, 0, v63
	v_pk_mul_f32 v[60:61], v[60:61], v[60:61]
	v_pk_mul_f32 v[62:63], v[62:63], v[62:63]
	v_cvt_pk_bf16_f32 v158, v60, v61
	v_cvt_pk_bf16_f32 v159, v62, v63
	ds_write_b64 v236, v[158:159] offset:7008
	v_max_f32_e32 v64, 0, v64
	v_max_f32_e32 v65, 0, v65
	v_max_f32_e32 v66, 0, v66
	v_max_f32_e32 v67, 0, v67
	v_pk_mul_f32 v[64:65], v[64:65], v[64:65]
	v_pk_mul_f32 v[66:67], v[66:67], v[66:67]
	v_cvt_pk_bf16_f32 v128, v64, v65
	v_cvt_pk_bf16_f32 v129, v66, v67
	ds_write_b64 v236, v[128:129] offset:9216
	v_max_f32_e32 v68, 0, v68
	v_max_f32_e32 v69, 0, v69
	v_max_f32_e32 v70, 0, v70
	v_max_f32_e32 v71, 0, v71
	v_pk_mul_f32 v[68:69], v[68:69], v[68:69]
	v_pk_mul_f32 v[70:71], v[70:71], v[70:71]
	v_cvt_pk_bf16_f32 v130, v68, v69
	v_cvt_pk_bf16_f32 v131, v70, v71
	ds_write_b64 v236, v[130:131] offset:9248
	v_max_f32_e32 v72, 0, v72
	v_max_f32_e32 v73, 0, v73
; DI unsigned pack2(float lo, float hi) { const f32x2c v = {lo, hi}; return __builtin_bit_cast(unsigned, __builtin_convertvector(v, bf16x2c)); }
; template <class Epi>
; DI void gemm_tile(char* smem, const bf16_t* __restrict__ A0, int lda0, int ksplit, const bf16_t* __restrict__ A1, int lda1,
;                   const bf16_t* __restrict__ Bt, int K, int row0, int col0, const Epi& epi, int tid) {
;     ...
;   for (int m = 0; m < 8; ++m)
; #pragma unroll
;     for (int n = 0; n < 4; ++n) epi(row0 + wr * 128 + m * 16 + fr, col0 + wc * 64 + n * 16 + fq * 4, acc[m][n]);
; }
; DI void st_bf16x4(bf16_t* o, f32x4 v) { u32x2 q; q.x = pack2(v[0], v[1]); q.y = pack2(v[2], v[3]); *(u32x2*)o = q; }
	v_max_f32_e32 v74, 0, v74
	v_max_f32_e32 v75, 0, v75
	v_pk_mul_f32 v[72:73], v[72:73], v[72:73]
	v_pk_mul_f32 v[74:75], v[74:75], v[74:75]
	v_cvt_pk_bf16_f32 v132, v72, v73
	v_cvt_pk_bf16_f32 v133, v74, v75
	ds_write_b64 v236, v[132:133] offset:9280
	v_max_f32_e32 v76, 0, v76
	v_max_f32_e32 v77, 0, v77
	v_max_f32_e32 v78, 0, v78
	v_max_f32_e32 v79, 0, v79
	v_pk_mul_f32 v[76:77], v[76:77], v[76:77]
	v_pk_mul_f32 v[78:79], v[78:79], v[78:79]
	v_cvt_pk_bf16_f32 v134, v76, v77
	v_cvt_pk_bf16_f32 v135, v78, v79
	ds_write_b64 v236, v[134:135] offset:9312
	v_max_f32_e32 v80, 0, v80
	v_max_f32_e32 v81, 0, v81
	v_max_f32_e32 v82, 0, v82
	v_max_f32_e32 v83, 0, v83
	v_pk_mul_f32 v[80:81], v[80:81], v[80:81]
	v_pk_mul_f32 v[82:83], v[82:83], v[82:83]
	v_cvt_pk_bf16_f32 v136, v80, v81
	v_cvt_pk_bf16_f32 v137, v82, v83
	ds_write_b64 v236, v[136:137] offset:11520
	v_max_f32_e32 v84, 0, v84
	v_max_f32_e32 v85, 0, v85
	v_max_f32_e32 v86, 0, v86
	v_max_f32_e32 v87, 0, v87
	v_pk_mul_f32 v[84:85], v[84:85], v[84:85]
	v_pk_mul_f32 v[86:87], v[86:87], v[86:87]
	v_cvt_pk_bf16_f32 v138, v84, v85
	v_cvt_pk_bf16_f32 v139, v86, v87
	ds_write_b64 v236, v[138:139] offset:11552
	v_max_f32_e32 v88, 0, v88
	v_max_f32_e32 v89, 0, v89
	v_max_f32_e32 v90, 0, v90
	v_max_f32_e32 v91, 0, v91
	v_pk_mul_f32 v[88:89], v[88:89], v[88:89]
	v_pk_mul_f32 v[90:91], v[90:91], v[90:91]
	v_cvt_pk_bf16_f32 v140, v88, v89
	v_cvt_pk_bf16_f32 v141, v90, v91
	ds_write_b64 v236, v[140:141] offset:11584
	v_max_f32_e32 v92, 0, v92
	v_max_f32_e32 v93, 0, v93
	v_max_f32_e32 v94, 0, v94
	v_max_f32_e32 v95, 0, v95
	v_pk_mul_f32 v[92:93], v[92:93], v[92:93]
	v_pk_mul_f32 v[94:95], v[94:95], v[94:95]
	v_cvt_pk_bf16_f32 v142, v92, v93
	v_cvt_pk_bf16_f32 v143, v94, v95
	ds_write_b64 v236, v[142:143] offset:11616
	v_max_f32_e32 v96, 0, v96
	v_max_f32_e32 v97, 0, v97
	v_max_f32_e32 v98, 0, v98
	v_max_f32_e32 v99, 0, v99
	v_pk_mul_f32 v[96:97], v[96:97], v[96:97]
	v_pk_mul_f32 v[98:99], v[98:99], v[98:99]
	v_cvt_pk_bf16_f32 v144, v96, v97
	v_cvt_pk_bf16_f32 v145, v98, v99
	ds_write_b64 v236, v[144:145] offset:13824
	v_max_f32_e32 v100, 0, v100
	v_max_f32_e32 v101, 0, v101
	v_max_f32_e32 v102, 0, v102
	v_max_f32_e32 v103, 0, v103
	v_pk_mul_f32 v[100:101], v[100:101], v[100:101]
	v_pk_mul_f32 v[102:103], v[102:103], v[102:103]
	v_cvt_pk_bf16_f32 v146, v100, v101
	v_cvt_pk_bf16_f32 v147, v102, v103
	ds_write_b64 v236, v[146:147] offset:13856
	v_max_f32_e32 v104, 0, v104
	v_max_f32_e32 v105, 0, v105
	v_max_f32_e32 v106, 0, v106
	v_max_f32_e32 v107, 0, v107
	v_pk_mul_f32 v[104:105], v[104:105], v[104:105]
	v_pk_mul_f32 v[106:107], v[106:107], v[106:107]
	v_cvt_pk_bf16_f32 v148, v104, v105
	v_cvt_pk_bf16_f32 v149, v106, v107
	ds_write_b64 v236, v[148:149] offset:13888
	v_max_f32_e32 v108, 0, v108
	v_max_f32_e32 v109, 0, v109
	v_max_f32_e32 v110, 0, v110
	v_max_f32_e32 v111, 0, v111
	v_pk_mul_f32 v[108:109], v[108:109], v[108:109]
	v_pk_mul_f32 v[110:111], v[110:111], v[110:111]
	v_cvt_pk_bf16_f32 v150, v108, v109
	v_cvt_pk_bf16_f32 v151, v110, v111
	ds_write_b64 v236, v[150:151] offset:13920
	v_max_f32_e32 v112, 0, v112
	v_max_f32_e32 v113, 0, v113
	v_max_f32_e32 v114, 0, v114
	v_max_f32_e32 v115, 0, v115
	v_pk_mul_f32 v[112:113], v[112:113], v[112:113]
	v_pk_mul_f32 v[114:115], v[114:115], v[114:115]
	v_cvt_pk_bf16_f32 v152, v112, v113
	v_cvt_pk_bf16_f32 v153, v114, v115
	ds_write_b64 v236, v[152:153] offset:16128
	v_max_f32_e32 v116, 0, v116
	v_max_f32_e32 v117, 0, v117
	v_max_f32_e32 v118, 0, v118
	v_max_f32_e32 v119, 0, v119
	v_pk_mul_f32 v[116:117], v[116:117], v[116:117]
	v_pk_mul_f32 v[118:119], v[118:119], v[118:119]
	v_cvt_pk_bf16_f32 v154, v116, v117
	v_cvt_pk_bf16_f32 v155, v118, v119
	ds_write_b64 v236, v[154:155] offset:16160
	v_max_f32_e32 v120, 0, v120
	v_max_f32_e32 v121, 0, v121
	v_max_f32_e32 v122, 0, v122
	v_max_f32_e32 v123, 0, v123
	v_pk_mul_f32 v[120:121], v[120:121], v[120:121]
	v_pk_mul_f32 v[122:123], v[122:123], v[122:123]
	v_cvt_pk_bf16_f32 v156, v120, v121
	v_cvt_pk_bf16_f32 v157, v122, v123
	ds_write_b64 v236, v[156:157] offset:16192
	v_max_f32_e32 v124, 0, v124
	v_max_f32_e32 v125, 0, v125
	v_max_f32_e32 v126, 0, v126
	v_max_f32_e32 v127, 0, v127
	v_pk_mul_f32 v[124:125], v[124:125], v[124:125]
	v_pk_mul_f32 v[126:127], v[126:127], v[126:127]
	v_cvt_pk_bf16_f32 v158, v124, v125
	v_cvt_pk_bf16_f32 v159, v126, v127
	ds_write_b64 v236, v[158:159] offset:16224
	s_waitcnt lgkmcnt(0)
; template <class Epi>
; DI void gemm_tile(char* smem, const bf16_t* __restrict__ A0, int lda0, int ksplit, const bf16_t* __restrict__ A1, int lda1,
;                   const bf16_t* __restrict__ Bt, int K, int row0, int col0, const Epi& epi, int tid) {
;     ...
;   for (int m = 0; m < 8; ++m)
; #pragma unroll
;     for (int n = 0; n < 4; ++n) epi(row0 + wr * 128 + m * 16 + fr, col0 + wc * 64 + n * 16 + fq * 4, acc[m][n]);
; template <class Epi>
; DI void gemm_phase(char* smem, const bf16_t* A0, int lda0, int ksplit, const bf16_t* A1, int lda1, const bf16_t* Bt, int K, int nN, const Epi& epi, int tid) {
;     ...
;     for (int q = l; q < tot; q += L) { const int rgl = q / per, rem = q % per, ct = rem >> 3, rt = (x * 2 + rgl) * 8 + (rem & 7);
;       gemm_tile(smem, A0, lda0, ksplit, A1, lda1, Bt, K, rt * 256, ct * 128, epi, tid); }
	ds_read_b128 v[128:131], v237
	ds_read_b128 v[132:135], v237 offset:1152
	ds_read_b128 v[136:139], v237 offset:2304
	ds_read_b128 v[140:143], v237 offset:3456
	ds_read_b128 v[144:147], v237 offset:4608
	ds_read_b128 v[148:151], v237 offset:5760
	ds_read_b128 v[152:155], v237 offset:6912
	ds_read_b128 v[156:159], v237 offset:8064
	ds_read_b128 v[160:163], v237 offset:9216
	ds_read_b128 v[164:167], v237 offset:10368
	ds_read_b128 v[168:171], v237 offset:11520
	ds_read_b128 v[172:175], v237 offset:12672
	ds_read_b128 v[176:179], v237 offset:13824
	ds_read_b128 v[180:183], v237 offset:14976
	ds_read_b128 v[184:187], v237 offset:16128
	ds_read_b128 v[188:191], v237 offset:17280
	s_waitcnt lgkmcnt(15)
	global_store_dwordx4 v238, v[128:131], s[4:5] nt
	s_add_u32 s4, s4, 0x10000
	s_addc_u32 s5, s5, 0
	s_waitcnt lgkmcnt(14)
	global_store_dwordx4 v238, v[132:135], s[4:5] nt
	s_add_u32 s4, s4, 0x10000
	s_addc_u32 s5, s5, 0
	s_waitcnt lgkmcnt(13)
	global_store_dwordx4 v238, v[136:139], s[4:5] nt
	s_add_u32 s4, s4, 0x10000
	s_addc_u32 s5, s5, 0
	s_waitcnt lgkmcnt(12)
	global_store_dwordx4 v238, v[140:143], s[4:5] nt
	s_add_u32 s4, s4, 0x10000
	s_addc_u32 s5, s5, 0
	s_waitcnt lgkmcnt(11)
	global_store_dwordx4 v238, v[144:147], s[4:5] nt
	s_add_u32 s4, s4, 0x10000
	s_addc_u32 s5, s5, 0
	s_waitcnt lgkmcnt(10)
	global_store_dwordx4 v238, v[148:151], s[4:5] nt
	s_add_u32 s4, s4, 0x10000
	s_addc_u32 s5, s5, 0
	s_waitcnt lgkmcnt(9)
	global_store_dwordx4 v238, v[152:155], s[4:5] nt
	s_add_u32 s4, s4, 0x10000
	s_addc_u32 s5, s5, 0
	s_waitcnt lgkmcnt(8)
	global_store_dwordx4 v238, v[156:159], s[4:5] nt
	s_add_u32 s4, s4, 0x10000
	s_addc_u32 s5, s5, 0
	s_waitcnt lgkmcnt(7)
	global_store_dwordx4 v238, v[160:163], s[4:5] nt
	s_add_u32 s4, s4, 0x10000
	s_addc_u32 s5, s5, 0
	s_waitcnt lgkmcnt(6)
	global_store_dwordx4 v238, v[164:167], s[4:5] nt
	s_add_u32 s4, s4, 0x10000
	s_addc_u32 s5, s5, 0
	s_waitcnt lgkmcnt(5)
	global_store_dwordx4 v238, v[168:171], s[4:5] nt
	s_add_u32 s4, s4, 0x10000
	s_addc_u32 s5, s5, 0
	s_waitcnt lgkmcnt(4)
	global_store_dwordx4 v238, v[172:175], s[4:5] nt
	s_add_u32 s4, s4, 0x10000
	s_addc_u32 s5, s5, 0
	s_waitcnt lgkmcnt(3)
	global_store_dwordx4 v238, v[176:179], s[4:5] nt
	s_add_u32 s4, s4, 0x10000
	s_addc_u32 s5, s5, 0
	s_waitcnt lgkmcnt(2)
	global_store_dwordx4 v238, v[180:183], s[4:5] nt
	s_add_u32 s4, s4, 0x10000
	s_addc_u32 s5, s5, 0
	s_waitcnt lgkmcnt(1)
	global_store_dwordx4 v238, v[184:187], s[4:5] nt
	s_add_u32 s4, s4, 0x10000
	s_addc_u32 s5, s5, 0
	s_waitcnt lgkmcnt(0)
	global_store_dwordx4 v238, v[188:191], s[4:5] nt
	s_nop 1
	s_cmp_lt_u32 s72, 64
	s_cbranch_scc0 .Lg8_dynB
	s_waitcnt vmcnt(16)
	v_readfirstlane_b32 s12, v242
	s_nop 3
	s_add_u32 s12, s12, 64
	v_mov_b32_e32 v244, s12
	ds_write_b32 v243, v244
.Lg8_dynB:
	s_waitcnt lgkmcnt(0)
	s_barrier
	ds_read_b32 v244, v243
	s_waitcnt lgkmcnt(0)
	v_readfirstlane_b32 s17, v244
	s_nop 3
	s_branch .Lg8_tile

; template <class Epi>
; DI void gemm_phase(char* smem, const bf16_t* A0, int lda0, int ksplit, const bf16_t* A1, int lda1, const bf16_t* Bt, int K, int nN, const Epi& epi, int tid) {
;   const int G = gridDim.x;
;   if ((G & 7) == 0) {
;     const int x = blockIdx.x & 7, l = blockIdx.x >> 3, L = G >> 3, per = 8 * nN, tot = 2 * per;
;     for (int q = l; q < tot; q += L) { const int rgl = q / per, rem = q % per, ct = rem >> 3, rt = (x * 2 + rgl) * 8 + (rem & 7);
.Lg11_prio:
	s_lshr_b32 s101, s96, 3
	s_and_b32 s100, s96, 7
	s_lshl_b32 s100, s100, 1
	s_waitcnt lgkmcnt(0)
	s_lshl_b32 s26, s100, 1
	s_add_u32 s26, s26, 0x1fe00220
	s_add_u32 s6, s92, s26
	s_addc_u32 s7, s93, 0
	v_mov_b32_e32 v240, 0
	v_mov_b32_e32 v241, 1
	v_mov_b32_e32 v243, 0x13600

; template <class Epi>
; DI void gemm_phase(char* smem, const bf16_t* A0, int lda0, int ksplit, const bf16_t* A1, int lda1, const bf16_t* Bt, int K, int nN, const Epi& epi, int tid) {
;     ...
;     for (int q = l; q < tot; q += L) { const int rgl = q / per, rem = q % per, ct = rem >> 3, rt = (x * 2 + rgl) * 8 + (rem & 7);
;       gemm_tile(smem, A0, lda0, ksplit, A1, lda1, Bt, K, rt * 256, ct * 128, epi, tid); }
.Lg11_enext:
	s_cmp_lt_u32 s72, 64
	s_cbranch_scc0 .Lg11_dynB
	s_waitcnt vmcnt(16)
	v_readfirstlane_b32 s26, v242
	s_nop 3
	s_add_u32 s26, s26, 64
	v_mov_b32_e32 v244, s26
	ds_write_b32 v243, v244
.Lg11_dynB:
	s_waitcnt lgkmcnt(0)
	s_barrier
	ds_read_b32 v244, v243
	s_waitcnt lgkmcnt(0)
	v_readfirstlane_b32 s101, v244
	s_nop 3
	s_branch .Lg11_tile

; template <class Epi>
; DI void gemm_phase(char* smem, const bf16_t* A0, int lda0, int ksplit, const bf16_t* A1, int lda1, const bf16_t* Bt, int K, int nN, const Epi& epi, int tid) {
;   const int G = gridDim.x;
;   if ((G & 7) == 0) {
;     const int x = blockIdx.x & 7, l = blockIdx.x >> 3, L = G >> 3, per = 8 * nN, tot = 2 * per;
;     for (int q = l; q < tot; q += L) { const int rgl = q / per, rem = q % per, ct = rem >> 3, rt = (x * 2 + rgl) * 8 + (rem & 7);
.Lg17_prio:
	s_lshr_b32 s17, s96, 3
	s_and_b32 s20, s96, 7
	s_lshl_b32 s20, s20, 1
	s_waitcnt lgkmcnt(0)
	s_lshl_b32 s12, s20, 1
	s_add_u32 s12, s12, 0x1fe00320
	s_add_u32 s6, s92, s12
	s_addc_u32 s7, s93, 0
	v_mov_b32_e32 v240, 0
	v_mov_b32_e32 v241, 1
	v_mov_b32_e32 v243, 0x13600
